# yield points (every 8 MFMAs) also in the peeled first K iterations of P4 and P5, on top of v110
# baseline (speedup 1.0000x reference)
; #define PG8_STAGE(bufoff, gbase, voff) do { _Pragma("unroll") for (int _i = 0; _i < 2; ++_i) \
;         __builtin_amdgcn_global_load_lds((const unsigned*)((const char*)(gbase) + (voff)[_i]), (PG8_LAS unsigned*)(lds + (bufoff) + ldsw + _i * 8192), 16, 0, 0); } while (0)
; #define PG8_LDA(dst, b, h) do { _Pragma("unroll") for (int m = 0; m < 4; ++m) _Pragma("unroll") for (int k = 0; k < 2; ++k) dst[m][k] = *(const PG8_LAS bf16x8*)(lds + PG8_SA(b, h) + aoff + m * 2048 + k * 1024); } while (0)
; #define PG8_LDB(dst, b, h) do { _Pragma("unroll") for (int n = 0; n < 2; ++n) _Pragma("unroll") for (int k = 0; k < 2; ++k) dst[n][k] = *(const PG8_LAS bf16x8*)(lds + PG8_SB(b, h) + boff + n * 2048 + k * 1024); } while (0)
; #define PG8_WAIT_V(n) asm volatile("s_waitcnt vmcnt(" #n ")" ::: "memory")
; #define PG8_WAIT_L(n) asm volatile("s_waitcnt lgkmcnt(" #n ")" ::: "memory")
; #define PG8_BAR __builtin_amdgcn_s_barrier()
; template <class Epi, class Sched, bool ALIGN_EPI = false, bool SP2 = false, bool ABLK = false>
; __device__ __forceinline__ void gemm_phase(PG8_LAS unsigned char* lds, const Gemm g, const Sched& S, const Epi& E) {
;     ...
;         const char* nA = has_next ? (const char*)g.A + (size_t)nxt.pm * tstepA : cA; const char* nB = has_next ? (const char*)g.Bt + (size_t)nxt.pn * tstep : cB;
;         for (int t = 0; t < nt; t += 2) {
;             if constexpr (Epi::MID) { if (t == nt / 2) E.mid(acc, cur, wr, wc, fr, fq); }
;             const bool last = (t == nt - 2);
;             const char* a1 = cA + (size_t)(t + 1) * kstepA;
;             const char* a2 = last ? nA : cA + (size_t)(t + 2) * kstepA; const char* b2 = last ? nB : cB + (size_t)(t + 2) * kstep;
;             const char* a3 = a2 + kstepA; const char* b3 = b2 + kstep;
;             if (last && has_next) S.a_ready(nxt);
;             if constexpr (SP2) {
;             PG8_LDB(B0, 0, 0); PG8_LDB(B1, 0, 1); PG8_SCHED; PG8_LDA(At, 0, 0); PG8_STAGE(PG8_SA(1, 1), a1 + hstepA, voffA);
;             PG8_WAIT_V(8); PG8_WAIT_L(0); PG8_BAR; PG8_MMA(0, 0, At, B0); PG8_MMA(0, 1, At, B1); PG8_BAR; PG8_SCHED;
;             PG8_LDA(At, 0, 1); PG8_STAGE(PG8_SB(0, 0), b2, voffB); PG8_STAGE(PG8_SB(0, 1), b2 + hstep, voffB); PG8_STAGE(PG8_SA(0, 0), a2, voffA);
;             PG8_WAIT_V(8); PG8_WAIT_L(0); PG8_BAR; PG8_MMA(1, 0, At, B0); PG8_MMA(1, 1, At, B1); PG8_BAR; PG8_SCHED;
.LBB0_533:
	s_ashr_i32 s21, s20, 31
	s_lshl_b64 s[8:9], s[20:21], 19
	s_add_u32 s24, s10, s8
	s_addc_u32 s25, s11, s9
	s_and_b64 s[8:9], s[26:27], exec
	s_cselect_b32 s7, s25, s37
	s_cselect_b32 s21, s24, s36
	s_ashr_i32 s23, s22, 31
	s_lshl_b64 s[8:9], s[22:23], 19
	s_add_u32 s28, s52, s8
	s_addc_u32 s29, s53, s9
	s_and_b64 s[8:9], s[26:27], exec
	s_cselect_b32 s23, s29, s35
	s_cselect_b32 s31, s28, s34
	s_add_u32 s61, s34, 0x100
	s_addc_u32 s62, s35, 0
	s_add_u32 s8, s36, 0xc000
	s_addc_u32 s9, s37, 0
	s_mov_b32 s63, -2
	ds_read_b128 v[128:131], v143
	ds_read_b128 v[176:179], v143 offset:1024
	ds_read_b128 v[180:183], v143 offset:2048
	ds_read_b128 v[184:187], v143 offset:3072
	ds_read_b128 v[188:191], v167
	ds_read_b128 v[192:195], v167 offset:1024
	ds_read_b128 v[196:199], v167 offset:2048
	ds_read_b128 v[200:203], v167 offset:3072
	s_add_u32 s2, s8, 0x4000
	s_addc_u32 s34, s9, 0
	s_cmp_eq_u32 s63, 12
	s_cselect_b32 s38, s21, s2
	s_cselect_b32 s39, s7, s34
	s_cselect_b32 s36, s31, s61
	s_cselect_b32 s37, s23, s62
	s_add_u32 s34, s38, 0x8000
	s_addc_u32 s35, s39, 0
	v_lshl_add_u64 v[172:173], s[8:9], 0, v[162:163]
	v_lshl_add_u64 v[240:241], s[8:9], 0, v[164:165]
	ds_read_b128 v[204:207], v168
	ds_read_b128 v[208:211], v168 offset:1024
	ds_read_b128 v[212:215], v168 offset:2048
	ds_read_b128 v[216:219], v168 offset:3072
	ds_read_b128 v[220:223], v168 offset:4096
	ds_read_b128 v[224:227], v168 offset:5120
	ds_read_b128 v[228:231], v168 offset:6144
	ds_read_b128 v[232:235], v168 offset:7168
	s_mov_b32 m0, s58
	s_nop 0
	global_load_lds_dwordx4 v[172:173], off
	s_mov_b32 m0, s59
	s_nop 0
	global_load_lds_dwordx4 v[240:241], off
	s_waitcnt vmcnt(8)
	s_waitcnt lgkmcnt(0)
	s_barrier
	s_setprio 1
	s_waitcnt lgkmcnt(0)
	v_mfma_f32_16x16x32_bf16 v[124:127], v[128:131], v[204:207], 0
	v_mfma_f32_16x16x32_bf16 v[120:123], v[180:183], v[204:207], 0
	v_mfma_f32_16x16x32_bf16 v[108:111], v[128:131], v[212:215], 0
	v_mfma_f32_16x16x32_bf16 v[104:107], v[180:183], v[212:215], 0
	v_mfma_f32_16x16x32_bf16 v[92:95], v[128:131], v[220:223], 0
	v_mfma_f32_16x16x32_bf16 v[88:91], v[180:183], v[220:223], 0
	v_mfma_f32_16x16x32_bf16 v[76:79], v[128:131], v[228:231], 0
	v_mfma_f32_16x16x32_bf16 v[72:75], v[180:183], v[228:231], 0
	s_setprio 0
	s_setprio 1
	v_mfma_f32_16x16x32_bf16 v[124:127], v[176:179], v[208:211], v[124:127]
	v_mfma_f32_16x16x32_bf16 v[120:123], v[184:187], v[208:211], v[120:123]
	v_mfma_f32_16x16x32_bf16 v[108:111], v[176:179], v[216:219], v[108:111]
	v_mfma_f32_16x16x32_bf16 v[104:107], v[184:187], v[216:219], v[104:107]
	v_mfma_f32_16x16x32_bf16 v[92:95], v[176:179], v[224:227], v[92:95]
	v_mfma_f32_16x16x32_bf16 v[88:91], v[184:187], v[224:227], v[88:91]
	v_mfma_f32_16x16x32_bf16 v[76:79], v[176:179], v[232:235], v[76:79]
	v_mfma_f32_16x16x32_bf16 v[72:75], v[184:187], v[232:235], v[72:75]
	s_setprio 0
	s_setprio 1
	v_mfma_f32_16x16x32_bf16 v[116:119], v[188:191], v[204:207], 0
	v_mfma_f32_16x16x32_bf16 v[112:115], v[196:199], v[204:207], 0
	v_mfma_f32_16x16x32_bf16 v[100:103], v[188:191], v[212:215], 0
	v_mfma_f32_16x16x32_bf16 v[96:99], v[196:199], v[212:215], 0
	v_mfma_f32_16x16x32_bf16 v[84:87], v[188:191], v[220:223], 0
	v_mfma_f32_16x16x32_bf16 v[80:83], v[196:199], v[220:223], 0
	v_mfma_f32_16x16x32_bf16 v[68:71], v[188:191], v[228:231], 0
	v_mfma_f32_16x16x32_bf16 v[64:67], v[196:199], v[228:231], 0
	s_setprio 0
	s_setprio 1
	v_mfma_f32_16x16x32_bf16 v[116:119], v[192:195], v[208:211], v[116:119]
	v_mfma_f32_16x16x32_bf16 v[112:115], v[200:203], v[208:211], v[112:115]
	v_mfma_f32_16x16x32_bf16 v[100:103], v[192:195], v[216:219], v[100:103]
	v_mfma_f32_16x16x32_bf16 v[96:99], v[200:203], v[216:219], v[96:99]
	v_mfma_f32_16x16x32_bf16 v[84:87], v[192:195], v[224:227], v[84:87]
	v_mfma_f32_16x16x32_bf16 v[80:83], v[200:203], v[224:227], v[80:83]
	v_mfma_f32_16x16x32_bf16 v[68:71], v[192:195], v[232:235], v[68:71]
	v_mfma_f32_16x16x32_bf16 v[64:67], v[200:203], v[232:235], v[64:67]
	s_setprio 0
	s_barrier
	s_add_u32 s70, s36, 0x40000
	s_addc_u32 s71, s37, 0
	s_add_i32 s2, s57, s3
	v_lshl_add_u64 v[172:173], s[36:37], 0, v[136:137]
	v_lshl_add_u64 v[236:237], s[36:37], 0, v[132:133]
	v_lshl_add_u64 v[238:239], s[70:71], 0, v[136:137]
	v_lshl_add_u64 v[240:241], s[70:71], 0, v[132:133]
	v_lshl_add_u64 v[242:243], s[38:39], 0, v[138:139]
	v_lshl_add_u64 v[254:255], s[38:39], 0, v[134:135]
	ds_read_b128 v[204:207], v168 offset:16384
	ds_read_b128 v[208:211], v168 offset:17408
	ds_read_b128 v[212:215], v168 offset:18432
	ds_read_b128 v[216:219], v168 offset:19456
	ds_read_b128 v[220:223], v168 offset:20480
	ds_read_b128 v[224:227], v168 offset:21504
	ds_read_b128 v[228:231], v168 offset:22528
	ds_read_b128 v[232:235], v168 offset:23552
	s_mov_b32 m0, s60
	s_nop 0
	global_load_lds_dwordx4 v[172:173], off
	s_add_i32 m0, s60, 0x2000
	s_nop 0
	global_load_lds_dwordx4 v[236:237], off
	s_mov_b32 m0, s2
	s_nop 0
	global_load_lds_dwordx4 v[238:239], off
	s_add_i32 m0, s2, 0x2000
	s_nop 0
	global_load_lds_dwordx4 v[240:241], off
	s_mov_b32 m0, s40
	s_nop 0
	global_load_lds_dwordx4 v[242:243], off
	s_mov_b32 m0, s41
	s_nop 0
	global_load_lds_dwordx4 v[254:255], off
	s_waitcnt vmcnt(8)
	s_waitcnt lgkmcnt(0)
	s_barrier
; #define PG8_STAGE(bufoff, gbase, voff) do { _Pragma("unroll") for (int _i = 0; _i < 2; ++_i) \
;         __builtin_amdgcn_global_load_lds((const unsigned*)((const char*)(gbase) + (voff)[_i]), (PG8_LAS unsigned*)(lds + (bufoff) + ldsw + _i * 8192), 16, 0, 0); } while (0)
; #define PG8_LDA(dst, b, h) do { _Pragma("unroll") for (int m = 0; m < 4; ++m) _Pragma("unroll") for (int k = 0; k < 2; ++k) dst[m][k] = *(const PG8_LAS bf16x8*)(lds + PG8_SA(b, h) + aoff + m * 2048 + k * 1024); } while (0)
; #define PG8_LDB(dst, b, h) do { _Pragma("unroll") for (int n = 0; n < 2; ++n) _Pragma("unroll") for (int k = 0; k < 2; ++k) dst[n][k] = *(const PG8_LAS bf16x8*)(lds + PG8_SB(b, h) + boff + n * 2048 + k * 1024); } while (0)
; #define PG8_MMA(ai, bj, At, Bt) do { __builtin_amdgcn_s_setprio(1); _Pragma("unroll") for (int m = 0; m < 4; ++m) _Pragma("unroll") for (int n = 0; n < 2; ++n) _Pragma("unroll") for (int k = 0; k < 2; ++k) \
;         acc[ai][bj][m][n] = __builtin_amdgcn_mfma_f32_16x16x32_bf16(Bt[n][k], At[m][k], acc[ai][bj][m][n], 0, 0, 0); __builtin_amdgcn_s_setprio(0); } while (0)
; #define PG8_WAIT_V(n) asm volatile("s_waitcnt vmcnt(" #n ")" ::: "memory")
; #define PG8_WAIT_L(n) asm volatile("s_waitcnt lgkmcnt(" #n ")" ::: "memory")
; #define PG8_BAR __builtin_amdgcn_s_barrier()
; #define PG8_SCHED __builtin_amdgcn_sched_barrier(0)
; template <class Epi, class Sched, bool ALIGN_EPI = false, bool SP2 = false, bool ABLK = false>
; __device__ __forceinline__ void gemm_phase(PG8_LAS unsigned char* lds, const Gemm g, const Sched& S, const Epi& E) {
;     ...
;             PG8_WAIT_V(8); PG8_WAIT_L(0); PG8_BAR; PG8_MMA(1, 0, At, B0); PG8_MMA(1, 1, At, B1); PG8_BAR; PG8_SCHED;
;             PG8_LDB(B0, 1, 0); PG8_LDB(B1, 1, 1); PG8_SCHED; PG8_LDA(At, 1, 0); PG8_STAGE(PG8_SA(0, 1), a2 + hstepA, voffA);
;             PG8_WAIT_V(8); PG8_WAIT_L(0); PG8_BAR; PG8_MMA(0, 0, At, B0); PG8_MMA(0, 1, At, B1); PG8_BAR; PG8_SCHED;
	s_setprio 1
	s_waitcnt lgkmcnt(0)
	v_mfma_f32_16x16x32_bf16 v[60:63], v[128:131], v[204:207], 0
	v_mfma_f32_16x16x32_bf16 v[56:59], v[180:183], v[204:207], 0
	v_mfma_f32_16x16x32_bf16 v[44:47], v[128:131], v[212:215], 0
	v_mfma_f32_16x16x32_bf16 v[40:43], v[180:183], v[212:215], 0
	v_mfma_f32_16x16x32_bf16 v[28:31], v[128:131], v[220:223], 0
	v_mfma_f32_16x16x32_bf16 v[24:27], v[180:183], v[220:223], 0
	v_mfma_f32_16x16x32_bf16 v[12:15], v[128:131], v[228:231], 0
	v_mfma_f32_16x16x32_bf16 v[8:11], v[180:183], v[228:231], 0
	s_setprio 0
	s_setprio 1
	v_mfma_f32_16x16x32_bf16 v[60:63], v[176:179], v[208:211], v[60:63]
	v_mfma_f32_16x16x32_bf16 v[56:59], v[184:187], v[208:211], v[56:59]
	v_mfma_f32_16x16x32_bf16 v[44:47], v[176:179], v[216:219], v[44:47]
	v_mfma_f32_16x16x32_bf16 v[40:43], v[184:187], v[216:219], v[40:43]
	v_mfma_f32_16x16x32_bf16 v[28:31], v[176:179], v[224:227], v[28:31]
	v_mfma_f32_16x16x32_bf16 v[24:27], v[184:187], v[224:227], v[24:27]
	v_mfma_f32_16x16x32_bf16 v[12:15], v[176:179], v[232:235], v[12:15]
	v_mfma_f32_16x16x32_bf16 v[8:11], v[184:187], v[232:235], v[8:11]
	s_setprio 0
	s_setprio 1
	v_mfma_f32_16x16x32_bf16 v[52:55], v[188:191], v[204:207], 0
	v_mfma_f32_16x16x32_bf16 v[48:51], v[196:199], v[204:207], 0
	v_mfma_f32_16x16x32_bf16 v[36:39], v[188:191], v[212:215], 0
	v_mfma_f32_16x16x32_bf16 v[32:35], v[196:199], v[212:215], 0
	v_mfma_f32_16x16x32_bf16 v[20:23], v[188:191], v[220:223], 0
	v_mfma_f32_16x16x32_bf16 v[16:19], v[196:199], v[220:223], 0
	v_mfma_f32_16x16x32_bf16 v[4:7], v[188:191], v[228:231], 0
	v_mfma_f32_16x16x32_bf16 v[0:3], v[196:199], v[228:231], 0
	s_setprio 0
	s_setprio 1
	v_mfma_f32_16x16x32_bf16 v[52:55], v[192:195], v[208:211], v[52:55]
	v_mfma_f32_16x16x32_bf16 v[48:51], v[200:203], v[208:211], v[48:51]
	v_mfma_f32_16x16x32_bf16 v[36:39], v[192:195], v[216:219], v[36:39]
	v_mfma_f32_16x16x32_bf16 v[32:35], v[200:203], v[216:219], v[32:35]
	v_mfma_f32_16x16x32_bf16 v[20:23], v[192:195], v[224:227], v[20:23]
	v_mfma_f32_16x16x32_bf16 v[16:19], v[200:203], v[224:227], v[16:19]
	v_mfma_f32_16x16x32_bf16 v[4:7], v[192:195], v[232:235], v[4:7]
	v_mfma_f32_16x16x32_bf16 v[0:3], v[200:203], v[232:235], v[0:3]
	s_setprio 0
	s_barrier
	s_add_i32 s2, 0, 0x18000
	v_add_u32_e32 v171, s2, v166
	s_add_i32 s70, 0, 0x1c000
	ds_read_b128 v[128:131], v171
	ds_read_b128 v[176:179], v171 offset:1024
	ds_read_b128 v[180:183], v171 offset:2048
	ds_read_b128 v[184:187], v171 offset:3072
	v_add_u32_e32 v171, s70, v166
	ds_read_b128 v[188:191], v171
	ds_read_b128 v[192:195], v171 offset:1024
	ds_read_b128 v[196:199], v171 offset:2048
	ds_read_b128 v[200:203], v171 offset:3072
	s_add_u32 s38, s38, 0x4000
	s_addc_u32 s39, s39, 0
	v_lshl_add_u64 v[238:239], s[38:39], 0, v[138:139]
	v_lshl_add_u64 v[240:241], s[38:39], 0, v[134:135]
	ds_read_b128 v[204:207], v168 offset:32768
	ds_read_b128 v[208:211], v168 offset:33792
	ds_read_b128 v[212:215], v168 offset:34816
	ds_read_b128 v[216:219], v168 offset:35840
	ds_read_b128 v[220:223], v168 offset:36864
	ds_read_b128 v[224:227], v168 offset:37888
	ds_read_b128 v[228:231], v168 offset:38912
	ds_read_b128 v[232:235], v168 offset:39936
	s_mov_b32 m0, s44
	s_nop 0
	global_load_lds_dwordx4 v[238:239], off
	s_mov_b32 m0, s45
	s_nop 0
	global_load_lds_dwordx4 v[240:241], off
	s_waitcnt vmcnt(8)
	s_waitcnt lgkmcnt(0)
	s_barrier
	s_setprio 1
	s_waitcnt lgkmcnt(0)
	v_mfma_f32_16x16x32_bf16 v[124:127], v[128:131], v[204:207], v[124:127]
	v_mfma_f32_16x16x32_bf16 v[120:123], v[180:183], v[204:207], v[120:123]
	v_mfma_f32_16x16x32_bf16 v[108:111], v[128:131], v[212:215], v[108:111]
	v_mfma_f32_16x16x32_bf16 v[104:107], v[180:183], v[212:215], v[104:107]
	v_mfma_f32_16x16x32_bf16 v[92:95], v[128:131], v[220:223], v[92:95]
	v_mfma_f32_16x16x32_bf16 v[88:91], v[180:183], v[220:223], v[88:91]
	v_mfma_f32_16x16x32_bf16 v[76:79], v[128:131], v[228:231], v[76:79]
	v_mfma_f32_16x16x32_bf16 v[72:75], v[180:183], v[228:231], v[72:75]
	s_setprio 0
	s_setprio 1
	v_mfma_f32_16x16x32_bf16 v[124:127], v[176:179], v[208:211], v[124:127]
	v_mfma_f32_16x16x32_bf16 v[120:123], v[184:187], v[208:211], v[120:123]
	v_mfma_f32_16x16x32_bf16 v[108:111], v[176:179], v[216:219], v[108:111]
	v_mfma_f32_16x16x32_bf16 v[104:107], v[184:187], v[216:219], v[104:107]
	v_mfma_f32_16x16x32_bf16 v[92:95], v[176:179], v[224:227], v[92:95]
	v_mfma_f32_16x16x32_bf16 v[88:91], v[184:187], v[224:227], v[88:91]
	v_mfma_f32_16x16x32_bf16 v[76:79], v[176:179], v[232:235], v[76:79]
	v_mfma_f32_16x16x32_bf16 v[72:75], v[184:187], v[232:235], v[72:75]
	s_setprio 0
	s_setprio 1
	v_mfma_f32_16x16x32_bf16 v[116:119], v[188:191], v[204:207], v[116:119]
	v_mfma_f32_16x16x32_bf16 v[112:115], v[196:199], v[204:207], v[112:115]
	v_mfma_f32_16x16x32_bf16 v[100:103], v[188:191], v[212:215], v[100:103]
	v_mfma_f32_16x16x32_bf16 v[96:99], v[196:199], v[212:215], v[96:99]
	v_mfma_f32_16x16x32_bf16 v[84:87], v[188:191], v[220:223], v[84:87]
	v_mfma_f32_16x16x32_bf16 v[80:83], v[196:199], v[220:223], v[80:83]
	v_mfma_f32_16x16x32_bf16 v[68:71], v[188:191], v[228:231], v[68:71]
	v_mfma_f32_16x16x32_bf16 v[64:67], v[196:199], v[228:231], v[64:67]
	s_setprio 0
	s_setprio 1
	v_mfma_f32_16x16x32_bf16 v[116:119], v[192:195], v[208:211], v[116:119]
	v_mfma_f32_16x16x32_bf16 v[112:115], v[200:203], v[208:211], v[112:115]
	v_mfma_f32_16x16x32_bf16 v[100:103], v[192:195], v[216:219], v[100:103]
	v_mfma_f32_16x16x32_bf16 v[96:99], v[200:203], v[216:219], v[96:99]
	v_mfma_f32_16x16x32_bf16 v[84:87], v[192:195], v[224:227], v[84:87]
	v_mfma_f32_16x16x32_bf16 v[80:83], v[200:203], v[224:227], v[80:83]
	v_mfma_f32_16x16x32_bf16 v[68:71], v[192:195], v[232:235], v[68:71]
	v_mfma_f32_16x16x32_bf16 v[64:67], v[200:203], v[232:235], v[64:67]
	s_setprio 0
	s_barrier
; #define PG8_STAGE(bufoff, gbase, voff) do { _Pragma("unroll") for (int _i = 0; _i < 2; ++_i) \
;         __builtin_amdgcn_global_load_lds((const unsigned*)((const char*)(gbase) + (voff)[_i]), (PG8_LAS unsigned*)(lds + (bufoff) + ldsw + _i * 8192), 16, 0, 0); } while (0)
; #define PG8_LDA(dst, b, h) do { _Pragma("unroll") for (int m = 0; m < 4; ++m) _Pragma("unroll") for (int k = 0; k < 2; ++k) dst[m][k] = *(const PG8_LAS bf16x8*)(lds + PG8_SA(b, h) + aoff + m * 2048 + k * 1024); } while (0)
; #define PG8_MMA(ai, bj, At, Bt) do { __builtin_amdgcn_s_setprio(1); _Pragma("unroll") for (int m = 0; m < 4; ++m) _Pragma("unroll") for (int n = 0; n < 2; ++n) _Pragma("unroll") for (int k = 0; k < 2; ++k) \
;         acc[ai][bj][m][n] = __builtin_amdgcn_mfma_f32_16x16x32_bf16(Bt[n][k], At[m][k], acc[ai][bj][m][n], 0, 0, 0); __builtin_amdgcn_s_setprio(0); } while (0)
; #define PG8_WAIT_V(n) asm volatile("s_waitcnt vmcnt(" #n ")" ::: "memory")
; #define PG8_WAIT_L(n) asm volatile("s_waitcnt lgkmcnt(" #n ")" ::: "memory")
; #define PG8_BAR __builtin_amdgcn_s_barrier()
; #define PG8_SCHED __builtin_amdgcn_sched_barrier(0)
; template <class Epi, class Sched, bool ALIGN_EPI = false, bool SP2 = false, bool ABLK = false>
; __device__ __forceinline__ void gemm_phase(PG8_LAS unsigned char* lds, const Gemm g, const Sched& S, const Epi& E) {
;     ...
;         for (int t = 0; t < nt; t += 2) {
;     ...
;             PG8_LDA(At, 1, 1); PG8_STAGE(PG8_SB(1, 0), b3, voffB); PG8_STAGE(PG8_SB(1, 1), b3 + hstep, voffB); PG8_STAGE(PG8_SA(1, 0), a3, voffA);
;             PG8_WAIT_V(8); PG8_WAIT_L(0); PG8_BAR; PG8_MMA(1, 0, At, B0); PG8_MMA(1, 1, At, B1); PG8_BAR; PG8_SCHED;
	s_add_i32 s2, s2, s3
	s_add_u32 s36, s36, 0x40080
	s_addc_u32 s37, s37, 0
	v_lshl_add_u64 v[172:173], v[172:173], 0, s[16:17]
	v_lshl_add_u64 v[236:237], v[236:237], 0, s[16:17]
	v_lshl_add_u64 v[238:239], s[36:37], 0, v[136:137]
	v_lshl_add_u64 v[240:241], s[36:37], 0, v[132:133]
	v_lshl_add_u64 v[242:243], s[34:35], 0, v[138:139]
	v_lshl_add_u64 v[254:255], s[34:35], 0, v[134:135]
	ds_read_b128 v[204:207], v168 offset:49152
	ds_read_b128 v[208:211], v168 offset:50176
	ds_read_b128 v[212:215], v168 offset:51200
	ds_read_b128 v[216:219], v168 offset:52224
	ds_read_b128 v[220:223], v168 offset:53248
	ds_read_b128 v[224:227], v168 offset:54272
	ds_read_b128 v[228:231], v168 offset:55296
	ds_read_b128 v[232:235], v168 offset:56320
	s_mov_b32 m0, s2
	s_nop 0
	global_load_lds_dwordx4 v[172:173], off
	s_add_i32 m0, s2, 0x2000
	s_nop 0
	global_load_lds_dwordx4 v[236:237], off
	s_add_i32 s2, s70, s3
	s_mov_b32 m0, s2
	s_nop 0
	global_load_lds_dwordx4 v[238:239], off
	s_add_i32 m0, s2, 0x2000
	s_nop 0
	global_load_lds_dwordx4 v[240:241], off
	s_mov_b32 m0, s55
	s_nop 0
	global_load_lds_dwordx4 v[242:243], off
	s_mov_b32 m0, s56
	s_nop 0
	global_load_lds_dwordx4 v[254:255], off
	s_waitcnt vmcnt(8)
	s_waitcnt lgkmcnt(0)
	s_barrier
	s_setprio 1
	s_waitcnt lgkmcnt(0)
	v_mfma_f32_16x16x32_bf16 v[60:63], v[128:131], v[204:207], v[60:63]
	v_mfma_f32_16x16x32_bf16 v[56:59], v[180:183], v[204:207], v[56:59]
	v_mfma_f32_16x16x32_bf16 v[44:47], v[128:131], v[212:215], v[44:47]
	v_mfma_f32_16x16x32_bf16 v[40:43], v[180:183], v[212:215], v[40:43]
	v_mfma_f32_16x16x32_bf16 v[28:31], v[128:131], v[220:223], v[28:31]
	v_mfma_f32_16x16x32_bf16 v[24:27], v[180:183], v[220:223], v[24:27]
	v_mfma_f32_16x16x32_bf16 v[12:15], v[128:131], v[228:231], v[12:15]
	v_mfma_f32_16x16x32_bf16 v[8:11], v[180:183], v[228:231], v[8:11]
	s_setprio 0
	s_setprio 1
	v_mfma_f32_16x16x32_bf16 v[60:63], v[176:179], v[208:211], v[60:63]
	v_mfma_f32_16x16x32_bf16 v[56:59], v[184:187], v[208:211], v[56:59]
	v_mfma_f32_16x16x32_bf16 v[44:47], v[176:179], v[216:219], v[44:47]
	v_mfma_f32_16x16x32_bf16 v[40:43], v[184:187], v[216:219], v[40:43]
	v_mfma_f32_16x16x32_bf16 v[28:31], v[176:179], v[224:227], v[28:31]
	v_mfma_f32_16x16x32_bf16 v[24:27], v[184:187], v[224:227], v[24:27]
	v_mfma_f32_16x16x32_bf16 v[12:15], v[176:179], v[232:235], v[12:15]
	v_mfma_f32_16x16x32_bf16 v[8:11], v[184:187], v[232:235], v[8:11]
	s_setprio 0
	s_setprio 1
	v_mfma_f32_16x16x32_bf16 v[52:55], v[188:191], v[204:207], v[52:55]
	v_mfma_f32_16x16x32_bf16 v[48:51], v[196:199], v[204:207], v[48:51]
	v_mfma_f32_16x16x32_bf16 v[36:39], v[188:191], v[212:215], v[36:39]
	v_mfma_f32_16x16x32_bf16 v[32:35], v[196:199], v[212:215], v[32:35]
	v_mfma_f32_16x16x32_bf16 v[20:23], v[188:191], v[220:223], v[20:23]
	v_mfma_f32_16x16x32_bf16 v[16:19], v[196:199], v[220:223], v[16:19]
	v_mfma_f32_16x16x32_bf16 v[4:7], v[188:191], v[228:231], v[4:7]
	v_mfma_f32_16x16x32_bf16 v[0:3], v[196:199], v[228:231], v[0:3]
	s_setprio 0
	s_setprio 1
	v_mfma_f32_16x16x32_bf16 v[52:55], v[192:195], v[208:211], v[52:55]
	v_mfma_f32_16x16x32_bf16 v[48:51], v[200:203], v[208:211], v[48:51]
	v_mfma_f32_16x16x32_bf16 v[36:39], v[192:195], v[216:219], v[36:39]
	v_mfma_f32_16x16x32_bf16 v[32:35], v[200:203], v[216:219], v[32:35]
	v_mfma_f32_16x16x32_bf16 v[20:23], v[192:195], v[224:227], v[20:23]
	v_mfma_f32_16x16x32_bf16 v[16:19], v[200:203], v[224:227], v[16:19]
	v_mfma_f32_16x16x32_bf16 v[4:7], v[192:195], v[232:235], v[4:7]
	v_mfma_f32_16x16x32_bf16 v[0:3], v[200:203], v[232:235], v[0:3]
	s_setprio 0
	s_barrier
	s_add_i32 s63, s63, 2
	s_add_u32 s61, s61, 0x100
	s_addc_u32 s62, s62, 0
	s_add_u32 s8, s8, 0x10000
	s_addc_u32 s9, s9, 0
	s_cmp_gt_u32 s63, 13
	s_cbranch_scc0 .LBB0_534
	s_branch .Lp4_kdone

; #define PG8_STAGE(bufoff, gbase, voff) do { _Pragma("unroll") for (int _i = 0; _i < 2; ++_i) \
;         __builtin_amdgcn_global_load_lds((const unsigned*)((const char*)(gbase) + (voff)[_i]), (PG8_LAS unsigned*)(lds + (bufoff) + ldsw + _i * 8192), 16, 0, 0); } while (0)
; #define PG8_LDA(dst, b, h) do { _Pragma("unroll") for (int m = 0; m < 4; ++m) _Pragma("unroll") for (int k = 0; k < 2; ++k) dst[m][k] = *(const PG8_LAS bf16x8*)(lds + PG8_SA(b, h) + aoff + m * 2048 + k * 1024); } while (0)
; #define PG8_LDB(dst, b, h) do { _Pragma("unroll") for (int n = 0; n < 2; ++n) _Pragma("unroll") for (int k = 0; k < 2; ++k) dst[n][k] = *(const PG8_LAS bf16x8*)(lds + PG8_SB(b, h) + boff + n * 2048 + k * 1024); } while (0)
; #define PG8_WAIT_V(n) asm volatile("s_waitcnt vmcnt(" #n ")" ::: "memory")
; #define PG8_WAIT_L(n) asm volatile("s_waitcnt lgkmcnt(" #n ")" ::: "memory")
; #define PG8_BAR __builtin_amdgcn_s_barrier()
; template <class Epi, class Sched, bool ALIGN_EPI = false, bool SP2 = false, bool ABLK = false>
; __device__ __forceinline__ void gemm_phase(PG8_LAS unsigned char* lds, const Gemm g, const Sched& S, const Epi& E) {
;     ...
;         const char* nA = has_next ? (const char*)g.A + (size_t)nxt.pm * tstepA : cA; const char* nB = has_next ? (const char*)g.Bt + (size_t)nxt.pn * tstep : cB;
;         for (int t = 0; t < nt; t += 2) {
;             if constexpr (Epi::MID) { if (t == nt / 2) E.mid(acc, cur, wr, wc, fr, fq); }
;             const bool last = (t == nt - 2);
;             const char* a1 = cA + (size_t)(t + 1) * kstepA;
;             const char* a2 = last ? nA : cA + (size_t)(t + 2) * kstepA; const char* b2 = last ? nB : cB + (size_t)(t + 2) * kstep;
;             const char* a3 = a2 + kstepA; const char* b3 = b2 + kstep;
;             if (last && has_next) S.a_ready(nxt);
;             if constexpr (SP2) {
;             PG8_LDB(B0, 0, 0); PG8_LDB(B1, 0, 1); PG8_SCHED; PG8_LDA(At, 0, 0); PG8_STAGE(PG8_SA(1, 1), a1 + hstepA, voffA);
;             PG8_WAIT_V(8); PG8_WAIT_L(0); PG8_BAR; PG8_MMA(0, 0, At, B0); PG8_MMA(0, 1, At, B1); PG8_BAR; PG8_SCHED;
;             PG8_LDA(At, 0, 1); PG8_STAGE(PG8_SB(0, 0), b2, voffB); PG8_STAGE(PG8_SB(0, 1), b2 + hstep, voffB); PG8_STAGE(PG8_SA(0, 0), a2, voffA);
;             PG8_WAIT_V(8); PG8_WAIT_L(0); PG8_BAR; PG8_MMA(1, 0, At, B0); PG8_MMA(1, 1, At, B1); PG8_BAR; PG8_SCHED;
.LBB0_577:
	s_ashr_i32 s21, s20, 31
	s_lshl_b64 s[24:25], s[20:21], 21
	s_add_u32 s24, s42, s24
	s_addc_u32 s25, s43, s25
	s_and_b64 s[28:29], s[26:27], exec
	s_cselect_b32 s21, s25, s37
	s_cselect_b32 s31, s24, s36
	s_ashr_i32 s23, s22, 31
	s_lshl_b64 s[28:29], s[22:23], 21
	s_add_u32 s28, s50, s28
	s_addc_u32 s29, s51, s29
	s_and_b64 s[38:39], s[26:27], exec
	s_cselect_b32 s23, s29, s35
	s_cselect_b32 s61, s28, s34
	s_add_u32 s62, s34, 0x100
	s_addc_u32 s63, s35, 0
	s_add_u32 s34, s36, 0xc000
	s_addc_u32 s35, s37, 0
	s_mov_b32 s64, -2
	ds_read_b128 v[142:145], v151
	ds_read_b128 v[154:157], v151 offset:1024
	ds_read_b128 v[158:161], v151 offset:2048
	ds_read_b128 v[162:165], v151 offset:3072
	ds_read_b128 v[166:169], v152
	ds_read_b128 v[170:173], v152 offset:1024
	ds_read_b128 v[174:177], v152 offset:2048
	ds_read_b128 v[178:181], v152 offset:3072
	s_add_u32 s36, s34, 0x4000
	s_addc_u32 s37, s35, 0
	s_cmp_eq_u32 s64, 60
	s_cselect_b32 s40, s31, s36
	s_cselect_b32 s41, s21, s37
	s_cselect_b32 s38, s61, s62
	s_cselect_b32 s39, s23, s63
	s_add_u32 s36, s40, 0x8000
	s_addc_u32 s37, s41, 0
	v_lshl_add_u64 v[146:147], s[34:35], 0, v[138:139]
	s_add_i32 m0, s45, 0xc000
	ds_read_b128 v[182:185], v153
	ds_read_b128 v[186:189], v153 offset:1024
	ds_read_b128 v[190:193], v153 offset:2048
	ds_read_b128 v[194:197], v153 offset:3072
	ds_read_b128 v[198:201], v153 offset:4096
	ds_read_b128 v[202:205], v153 offset:5120
	ds_read_b128 v[206:209], v153 offset:6144
	ds_read_b128 v[210:213], v153 offset:7168
	global_load_lds_dwordx4 v[146:147], off
	v_lshl_add_u64 v[146:147], s[34:35], 0, v[140:141]
	s_add_i32 m0, s45, 0xe000
	s_nop 0
	global_load_lds_dwordx4 v[146:147], off
	s_waitcnt vmcnt(8)
	s_waitcnt lgkmcnt(0)
	s_barrier
	s_setprio 1
	s_waitcnt lgkmcnt(0)
	v_mfma_f32_16x16x32_bf16 v[124:127], v[142:145], v[182:185], 0
	v_mfma_f32_16x16x32_bf16 v[120:123], v[158:161], v[182:185], 0
	v_mfma_f32_16x16x32_bf16 v[116:119], v[142:145], v[190:193], 0
	v_mfma_f32_16x16x32_bf16 v[112:115], v[158:161], v[190:193], 0
	v_mfma_f32_16x16x32_bf16 v[96:99], v[142:145], v[198:201], 0
	v_mfma_f32_16x16x32_bf16 v[88:91], v[158:161], v[198:201], 0
	v_mfma_f32_16x16x32_bf16 v[80:83], v[142:145], v[206:209], 0
	v_mfma_f32_16x16x32_bf16 v[72:75], v[158:161], v[206:209], 0
	s_setprio 0
	s_setprio 1
	v_mfma_f32_16x16x32_bf16 v[124:127], v[154:157], v[186:189], v[124:127]
	v_mfma_f32_16x16x32_bf16 v[120:123], v[162:165], v[186:189], v[120:123]
	v_mfma_f32_16x16x32_bf16 v[116:119], v[154:157], v[194:197], v[116:119]
	v_mfma_f32_16x16x32_bf16 v[112:115], v[162:165], v[194:197], v[112:115]
	v_mfma_f32_16x16x32_bf16 v[96:99], v[154:157], v[202:205], v[96:99]
	v_mfma_f32_16x16x32_bf16 v[88:91], v[162:165], v[202:205], v[88:91]
	v_mfma_f32_16x16x32_bf16 v[80:83], v[154:157], v[210:213], v[80:83]
	v_mfma_f32_16x16x32_bf16 v[72:75], v[162:165], v[210:213], v[72:75]
	s_setprio 0
	s_setprio 1
	v_mfma_f32_16x16x32_bf16 v[108:111], v[166:169], v[182:185], 0
	v_mfma_f32_16x16x32_bf16 v[104:107], v[174:177], v[182:185], 0
	v_mfma_f32_16x16x32_bf16 v[100:103], v[166:169], v[190:193], 0
	v_mfma_f32_16x16x32_bf16 v[92:95], v[174:177], v[190:193], 0
	v_mfma_f32_16x16x32_bf16 v[84:87], v[166:169], v[198:201], 0
	v_mfma_f32_16x16x32_bf16 v[76:79], v[174:177], v[198:201], 0
	v_mfma_f32_16x16x32_bf16 v[68:71], v[166:169], v[206:209], 0
	v_mfma_f32_16x16x32_bf16 v[64:67], v[174:177], v[206:209], 0
	s_setprio 0
	s_setprio 1
	v_mfma_f32_16x16x32_bf16 v[108:111], v[170:173], v[186:189], v[108:111]
	v_mfma_f32_16x16x32_bf16 v[104:107], v[178:181], v[186:189], v[104:107]
	v_mfma_f32_16x16x32_bf16 v[100:103], v[170:173], v[194:197], v[100:103]
	v_mfma_f32_16x16x32_bf16 v[92:95], v[178:181], v[194:197], v[92:95]
	v_mfma_f32_16x16x32_bf16 v[84:87], v[170:173], v[202:205], v[84:87]
	v_mfma_f32_16x16x32_bf16 v[76:79], v[178:181], v[202:205], v[76:79]
	v_mfma_f32_16x16x32_bf16 v[68:71], v[170:173], v[210:213], v[68:71]
	v_mfma_f32_16x16x32_bf16 v[64:67], v[178:181], v[210:213], v[64:67]
	s_setprio 0
	s_barrier
	s_add_i32 s65, s56, s44
	v_lshl_add_u64 v[146:147], s[38:39], 0, v[132:133]
	s_mov_b32 m0, s65
	ds_read_b128 v[182:185], v153 offset:16384
	ds_read_b128 v[186:189], v153 offset:17408
	ds_read_b128 v[190:193], v153 offset:18432
	ds_read_b128 v[194:197], v153 offset:19456
	ds_read_b128 v[198:201], v153 offset:20480
	ds_read_b128 v[202:205], v153 offset:21504
	ds_read_b128 v[206:209], v153 offset:22528
	ds_read_b128 v[210:213], v153 offset:23552
	global_load_lds_dwordx4 v[146:147], off
	s_add_i32 m0, s65, 0x2000
	s_add_u32 s70, s38, 0x100000
	v_lshl_add_u64 v[214:215], s[38:39], 0, v[128:129]
	s_addc_u32 s71, s39, 0
	s_add_i32 s65, s57, s44
	global_load_lds_dwordx4 v[214:215], off
	v_lshl_add_u64 v[216:217], s[70:71], 0, v[132:133]
	s_mov_b32 m0, s65
	s_nop 0
	global_load_lds_dwordx4 v[216:217], off
	v_lshl_add_u64 v[216:217], s[70:71], 0, v[128:129]
	s_add_i32 m0, s65, 0x2000
	s_nop 0
	global_load_lds_dwordx4 v[216:217], off
	v_lshl_add_u64 v[216:217], s[40:41], 0, v[134:135]
	s_mov_b32 m0, s45
	s_nop 0
	global_load_lds_dwordx4 v[216:217], off
	v_lshl_add_u64 v[216:217], s[40:41], 0, v[130:131]
	s_mov_b32 m0, s47
	s_nop 0
	global_load_lds_dwordx4 v[216:217], off
	s_waitcnt vmcnt(8)
	s_waitcnt lgkmcnt(0)
	s_barrier
; #define PG8_STAGE(bufoff, gbase, voff) do { _Pragma("unroll") for (int _i = 0; _i < 2; ++_i) \
;         __builtin_amdgcn_global_load_lds((const unsigned*)((const char*)(gbase) + (voff)[_i]), (PG8_LAS unsigned*)(lds + (bufoff) + ldsw + _i * 8192), 16, 0, 0); } while (0)
; #define PG8_LDA(dst, b, h) do { _Pragma("unroll") for (int m = 0; m < 4; ++m) _Pragma("unroll") for (int k = 0; k < 2; ++k) dst[m][k] = *(const PG8_LAS bf16x8*)(lds + PG8_SA(b, h) + aoff + m * 2048 + k * 1024); } while (0)
; #define PG8_LDB(dst, b, h) do { _Pragma("unroll") for (int n = 0; n < 2; ++n) _Pragma("unroll") for (int k = 0; k < 2; ++k) dst[n][k] = *(const PG8_LAS bf16x8*)(lds + PG8_SB(b, h) + boff + n * 2048 + k * 1024); } while (0)
; #define PG8_MMA(ai, bj, At, Bt) do { __builtin_amdgcn_s_setprio(1); _Pragma("unroll") for (int m = 0; m < 4; ++m) _Pragma("unroll") for (int n = 0; n < 2; ++n) _Pragma("unroll") for (int k = 0; k < 2; ++k) \
;         acc[ai][bj][m][n] = __builtin_amdgcn_mfma_f32_16x16x32_bf16(Bt[n][k], At[m][k], acc[ai][bj][m][n], 0, 0, 0); __builtin_amdgcn_s_setprio(0); } while (0)
; #define PG8_WAIT_V(n) asm volatile("s_waitcnt vmcnt(" #n ")" ::: "memory")
; #define PG8_WAIT_L(n) asm volatile("s_waitcnt lgkmcnt(" #n ")" ::: "memory")
; #define PG8_BAR __builtin_amdgcn_s_barrier()
; #define PG8_SCHED __builtin_amdgcn_sched_barrier(0)
; template <class Epi, class Sched, bool ALIGN_EPI = false, bool SP2 = false, bool ABLK = false>
; __device__ __forceinline__ void gemm_phase(PG8_LAS unsigned char* lds, const Gemm g, const Sched& S, const Epi& E) {
;     ...
;             PG8_WAIT_V(8); PG8_WAIT_L(0); PG8_BAR; PG8_MMA(1, 0, At, B0); PG8_MMA(1, 1, At, B1); PG8_BAR; PG8_SCHED;
;             PG8_LDB(B0, 1, 0); PG8_LDB(B1, 1, 1); PG8_SCHED; PG8_LDA(At, 1, 0); PG8_STAGE(PG8_SA(0, 1), a2 + hstepA, voffA);
;             PG8_WAIT_V(8); PG8_WAIT_L(0); PG8_BAR; PG8_MMA(0, 0, At, B0); PG8_MMA(0, 1, At, B1); PG8_BAR; PG8_SCHED;
	s_setprio 1
	s_waitcnt lgkmcnt(0)
	v_mfma_f32_16x16x32_bf16 v[60:63], v[142:145], v[182:185], 0
	v_mfma_f32_16x16x32_bf16 v[56:59], v[158:161], v[182:185], 0
	v_mfma_f32_16x16x32_bf16 v[48:51], v[142:145], v[190:193], 0
	v_mfma_f32_16x16x32_bf16 v[40:43], v[158:161], v[190:193], 0
	v_mfma_f32_16x16x32_bf16 v[32:35], v[142:145], v[198:201], 0
	v_mfma_f32_16x16x32_bf16 v[24:27], v[158:161], v[198:201], 0
	v_mfma_f32_16x16x32_bf16 v[16:19], v[142:145], v[206:209], 0
	v_mfma_f32_16x16x32_bf16 v[8:11], v[158:161], v[206:209], 0
	s_setprio 0
	s_setprio 1
	v_mfma_f32_16x16x32_bf16 v[60:63], v[154:157], v[186:189], v[60:63]
	v_mfma_f32_16x16x32_bf16 v[56:59], v[162:165], v[186:189], v[56:59]
	v_mfma_f32_16x16x32_bf16 v[48:51], v[154:157], v[194:197], v[48:51]
	v_mfma_f32_16x16x32_bf16 v[40:43], v[162:165], v[194:197], v[40:43]
	v_mfma_f32_16x16x32_bf16 v[32:35], v[154:157], v[202:205], v[32:35]
	v_mfma_f32_16x16x32_bf16 v[24:27], v[162:165], v[202:205], v[24:27]
	v_mfma_f32_16x16x32_bf16 v[16:19], v[154:157], v[210:213], v[16:19]
	v_mfma_f32_16x16x32_bf16 v[8:11], v[162:165], v[210:213], v[8:11]
	s_setprio 0
	s_setprio 1
	v_mfma_f32_16x16x32_bf16 v[52:55], v[166:169], v[182:185], 0
	v_mfma_f32_16x16x32_bf16 v[44:47], v[174:177], v[182:185], 0
	v_mfma_f32_16x16x32_bf16 v[36:39], v[166:169], v[190:193], 0
	v_mfma_f32_16x16x32_bf16 v[28:31], v[174:177], v[190:193], 0
	v_mfma_f32_16x16x32_bf16 v[20:23], v[166:169], v[198:201], 0
	v_mfma_f32_16x16x32_bf16 v[12:15], v[174:177], v[198:201], 0
	v_mfma_f32_16x16x32_bf16 v[4:7], v[166:169], v[206:209], 0
	v_mfma_f32_16x16x32_bf16 v[0:3], v[174:177], v[206:209], 0
	s_setprio 0
	s_setprio 1
	v_mfma_f32_16x16x32_bf16 v[52:55], v[170:173], v[186:189], v[52:55]
	v_mfma_f32_16x16x32_bf16 v[44:47], v[178:181], v[186:189], v[44:47]
	v_mfma_f32_16x16x32_bf16 v[36:39], v[170:173], v[194:197], v[36:39]
	v_mfma_f32_16x16x32_bf16 v[28:31], v[178:181], v[194:197], v[28:31]
	v_mfma_f32_16x16x32_bf16 v[20:23], v[170:173], v[202:205], v[20:23]
	v_mfma_f32_16x16x32_bf16 v[12:15], v[178:181], v[202:205], v[12:15]
	v_mfma_f32_16x16x32_bf16 v[4:7], v[170:173], v[210:213], v[4:7]
	v_mfma_f32_16x16x32_bf16 v[0:3], v[178:181], v[210:213], v[0:3]
	s_setprio 0
	s_barrier
	s_add_i32 s65, 0, 0x18000
	v_add_u32_e32 v136, s65, v150
	s_add_i32 s68, 0, 0x1c000
	ds_read_b128 v[142:145], v136
	ds_read_b128 v[154:157], v136 offset:1024
	ds_read_b128 v[158:161], v136 offset:2048
	ds_read_b128 v[162:165], v136 offset:3072
	v_add_u32_e32 v136, s68, v150
	ds_read_b128 v[166:169], v136
	ds_read_b128 v[170:173], v136 offset:1024
	ds_read_b128 v[174:177], v136 offset:2048
	ds_read_b128 v[178:181], v136 offset:3072
	s_add_u32 s40, s40, 0x4000
	s_addc_u32 s41, s41, 0
	s_mov_b32 m0, s48
	v_lshl_add_u64 v[216:217], s[40:41], 0, v[134:135]
	ds_read_b128 v[182:185], v153 offset:32768
	ds_read_b128 v[186:189], v153 offset:33792
	ds_read_b128 v[190:193], v153 offset:34816
	ds_read_b128 v[194:197], v153 offset:35840
	ds_read_b128 v[198:201], v153 offset:36864
	ds_read_b128 v[202:205], v153 offset:37888
	ds_read_b128 v[206:209], v153 offset:38912
	ds_read_b128 v[210:213], v153 offset:39936
	global_load_lds_dwordx4 v[216:217], off
	v_lshl_add_u64 v[216:217], s[40:41], 0, v[130:131]
	s_mov_b32 m0, s49
	s_nop 0
	global_load_lds_dwordx4 v[216:217], off
	s_waitcnt vmcnt(8)
	s_waitcnt lgkmcnt(0)
	s_barrier
	s_setprio 1
	s_waitcnt lgkmcnt(0)
	v_mfma_f32_16x16x32_bf16 v[124:127], v[142:145], v[182:185], v[124:127]
	v_mfma_f32_16x16x32_bf16 v[120:123], v[158:161], v[182:185], v[120:123]
	v_mfma_f32_16x16x32_bf16 v[116:119], v[142:145], v[190:193], v[116:119]
	v_mfma_f32_16x16x32_bf16 v[112:115], v[158:161], v[190:193], v[112:115]
	v_mfma_f32_16x16x32_bf16 v[96:99], v[142:145], v[198:201], v[96:99]
	v_mfma_f32_16x16x32_bf16 v[88:91], v[158:161], v[198:201], v[88:91]
	v_mfma_f32_16x16x32_bf16 v[80:83], v[142:145], v[206:209], v[80:83]
	v_mfma_f32_16x16x32_bf16 v[72:75], v[158:161], v[206:209], v[72:75]
	s_setprio 0
	s_setprio 1
	v_mfma_f32_16x16x32_bf16 v[124:127], v[154:157], v[186:189], v[124:127]
	v_mfma_f32_16x16x32_bf16 v[120:123], v[162:165], v[186:189], v[120:123]
	v_mfma_f32_16x16x32_bf16 v[116:119], v[154:157], v[194:197], v[116:119]
	v_mfma_f32_16x16x32_bf16 v[112:115], v[162:165], v[194:197], v[112:115]
	v_mfma_f32_16x16x32_bf16 v[96:99], v[154:157], v[202:205], v[96:99]
	v_mfma_f32_16x16x32_bf16 v[88:91], v[162:165], v[202:205], v[88:91]
	v_mfma_f32_16x16x32_bf16 v[80:83], v[154:157], v[210:213], v[80:83]
	v_mfma_f32_16x16x32_bf16 v[72:75], v[162:165], v[210:213], v[72:75]
	s_setprio 0
	s_setprio 1
	v_mfma_f32_16x16x32_bf16 v[108:111], v[166:169], v[182:185], v[108:111]
	v_mfma_f32_16x16x32_bf16 v[104:107], v[174:177], v[182:185], v[104:107]
	v_mfma_f32_16x16x32_bf16 v[100:103], v[166:169], v[190:193], v[100:103]
	v_mfma_f32_16x16x32_bf16 v[92:95], v[174:177], v[190:193], v[92:95]
	v_mfma_f32_16x16x32_bf16 v[84:87], v[166:169], v[198:201], v[84:87]
	v_mfma_f32_16x16x32_bf16 v[76:79], v[174:177], v[198:201], v[76:79]
	v_mfma_f32_16x16x32_bf16 v[68:71], v[166:169], v[206:209], v[68:71]
	v_mfma_f32_16x16x32_bf16 v[64:67], v[174:177], v[206:209], v[64:67]
	s_setprio 0
	s_setprio 1
	v_mfma_f32_16x16x32_bf16 v[108:111], v[170:173], v[186:189], v[108:111]
	v_mfma_f32_16x16x32_bf16 v[104:107], v[178:181], v[186:189], v[104:107]
	v_mfma_f32_16x16x32_bf16 v[100:103], v[170:173], v[194:197], v[100:103]
	v_mfma_f32_16x16x32_bf16 v[92:95], v[178:181], v[194:197], v[92:95]
	v_mfma_f32_16x16x32_bf16 v[84:87], v[170:173], v[202:205], v[84:87]
	v_mfma_f32_16x16x32_bf16 v[76:79], v[178:181], v[202:205], v[76:79]
	v_mfma_f32_16x16x32_bf16 v[68:71], v[170:173], v[210:213], v[68:71]
	v_mfma_f32_16x16x32_bf16 v[64:67], v[178:181], v[210:213], v[64:67]
	s_setprio 0
	s_barrier
; #define PG8_STAGE(bufoff, gbase, voff) do { _Pragma("unroll") for (int _i = 0; _i < 2; ++_i) \
;         __builtin_amdgcn_global_load_lds((const unsigned*)((const char*)(gbase) + (voff)[_i]), (PG8_LAS unsigned*)(lds + (bufoff) + ldsw + _i * 8192), 16, 0, 0); } while (0)
; #define PG8_LDA(dst, b, h) do { _Pragma("unroll") for (int m = 0; m < 4; ++m) _Pragma("unroll") for (int k = 0; k < 2; ++k) dst[m][k] = *(const PG8_LAS bf16x8*)(lds + PG8_SA(b, h) + aoff + m * 2048 + k * 1024); } while (0)
; #define PG8_MMA(ai, bj, At, Bt) do { __builtin_amdgcn_s_setprio(1); _Pragma("unroll") for (int m = 0; m < 4; ++m) _Pragma("unroll") for (int n = 0; n < 2; ++n) _Pragma("unroll") for (int k = 0; k < 2; ++k) \
;         acc[ai][bj][m][n] = __builtin_amdgcn_mfma_f32_16x16x32_bf16(Bt[n][k], At[m][k], acc[ai][bj][m][n], 0, 0, 0); __builtin_amdgcn_s_setprio(0); } while (0)
; #define PG8_WAIT_V(n) asm volatile("s_waitcnt vmcnt(" #n ")" ::: "memory")
; #define PG8_WAIT_L(n) asm volatile("s_waitcnt lgkmcnt(" #n ")" ::: "memory")
; #define PG8_BAR __builtin_amdgcn_s_barrier()
; #define PG8_SCHED __builtin_amdgcn_sched_barrier(0)
; template <class Epi, class Sched, bool ALIGN_EPI = false, bool SP2 = false, bool ABLK = false>
; __device__ __forceinline__ void gemm_phase(PG8_LAS unsigned char* lds, const Gemm g, const Sched& S, const Epi& E) {
;     ...
;         for (int t = 0; t < nt; t += 2) {
;     ...
;             PG8_LDA(At, 1, 1); PG8_STAGE(PG8_SB(1, 0), b3, voffB); PG8_STAGE(PG8_SB(1, 1), b3 + hstep, voffB); PG8_STAGE(PG8_SA(1, 0), a3, voffA);
;             PG8_WAIT_V(8); PG8_WAIT_L(0); PG8_BAR; PG8_MMA(1, 0, At, B0); PG8_MMA(1, 1, At, B1); PG8_BAR; PG8_SCHED;
	s_add_i32 s40, s65, s44
	v_lshl_add_u64 v[146:147], v[146:147], 0, s[4:5]
	s_mov_b32 m0, s40
	ds_read_b128 v[182:185], v153 offset:49152
	ds_read_b128 v[186:189], v153 offset:50176
	ds_read_b128 v[190:193], v153 offset:51200
	ds_read_b128 v[194:197], v153 offset:52224
	ds_read_b128 v[198:201], v153 offset:53248
	ds_read_b128 v[202:205], v153 offset:54272
	ds_read_b128 v[206:209], v153 offset:55296
	ds_read_b128 v[210:213], v153 offset:56320
	global_load_lds_dwordx4 v[146:147], off
	s_add_i32 m0, s40, 0x2000
	s_add_u32 s38, s38, 0x100080
	v_lshl_add_u64 v[146:147], v[214:215], 0, s[4:5]
	s_addc_u32 s39, s39, 0
	s_add_i32 s40, s68, s44
	global_load_lds_dwordx4 v[146:147], off
	v_lshl_add_u64 v[146:147], s[38:39], 0, v[132:133]
	s_mov_b32 m0, s40
	s_nop 0
	global_load_lds_dwordx4 v[146:147], off
	v_lshl_add_u64 v[146:147], s[38:39], 0, v[128:129]
	s_add_i32 m0, s40, 0x2000
	s_nop 0
	global_load_lds_dwordx4 v[146:147], off
	v_lshl_add_u64 v[146:147], s[36:37], 0, v[134:135]
	s_mov_b32 m0, s54
	s_nop 0
	global_load_lds_dwordx4 v[146:147], off
	v_lshl_add_u64 v[146:147], s[36:37], 0, v[130:131]
	s_mov_b32 m0, s55
	s_nop 0
	global_load_lds_dwordx4 v[146:147], off
	s_waitcnt vmcnt(8)
	s_waitcnt lgkmcnt(0)
	s_barrier
	s_setprio 1
	s_waitcnt lgkmcnt(0)
	v_mfma_f32_16x16x32_bf16 v[60:63], v[142:145], v[182:185], v[60:63]
	v_mfma_f32_16x16x32_bf16 v[56:59], v[158:161], v[182:185], v[56:59]
	v_mfma_f32_16x16x32_bf16 v[48:51], v[142:145], v[190:193], v[48:51]
	v_mfma_f32_16x16x32_bf16 v[40:43], v[158:161], v[190:193], v[40:43]
	v_mfma_f32_16x16x32_bf16 v[32:35], v[142:145], v[198:201], v[32:35]
	v_mfma_f32_16x16x32_bf16 v[24:27], v[158:161], v[198:201], v[24:27]
	v_mfma_f32_16x16x32_bf16 v[16:19], v[142:145], v[206:209], v[16:19]
	v_mfma_f32_16x16x32_bf16 v[8:11], v[158:161], v[206:209], v[8:11]
	s_setprio 0
	s_setprio 1
	v_mfma_f32_16x16x32_bf16 v[60:63], v[154:157], v[186:189], v[60:63]
	v_mfma_f32_16x16x32_bf16 v[56:59], v[162:165], v[186:189], v[56:59]
	v_mfma_f32_16x16x32_bf16 v[48:51], v[154:157], v[194:197], v[48:51]
	v_mfma_f32_16x16x32_bf16 v[40:43], v[162:165], v[194:197], v[40:43]
	v_mfma_f32_16x16x32_bf16 v[32:35], v[154:157], v[202:205], v[32:35]
	v_mfma_f32_16x16x32_bf16 v[24:27], v[162:165], v[202:205], v[24:27]
	v_mfma_f32_16x16x32_bf16 v[16:19], v[154:157], v[210:213], v[16:19]
	v_mfma_f32_16x16x32_bf16 v[8:11], v[162:165], v[210:213], v[8:11]
	s_setprio 0
	s_setprio 1
	v_mfma_f32_16x16x32_bf16 v[52:55], v[166:169], v[182:185], v[52:55]
	v_mfma_f32_16x16x32_bf16 v[44:47], v[174:177], v[182:185], v[44:47]
	v_mfma_f32_16x16x32_bf16 v[36:39], v[166:169], v[190:193], v[36:39]
	v_mfma_f32_16x16x32_bf16 v[28:31], v[174:177], v[190:193], v[28:31]
	v_mfma_f32_16x16x32_bf16 v[20:23], v[166:169], v[198:201], v[20:23]
	v_mfma_f32_16x16x32_bf16 v[12:15], v[174:177], v[198:201], v[12:15]
	v_mfma_f32_16x16x32_bf16 v[4:7], v[166:169], v[206:209], v[4:7]
	v_mfma_f32_16x16x32_bf16 v[0:3], v[174:177], v[206:209], v[0:3]
	s_setprio 0
	s_setprio 1
	v_mfma_f32_16x16x32_bf16 v[52:55], v[170:173], v[186:189], v[52:55]
	v_mfma_f32_16x16x32_bf16 v[44:47], v[178:181], v[186:189], v[44:47]
	v_mfma_f32_16x16x32_bf16 v[36:39], v[170:173], v[194:197], v[36:39]
	v_mfma_f32_16x16x32_bf16 v[28:31], v[178:181], v[194:197], v[28:31]
	v_mfma_f32_16x16x32_bf16 v[20:23], v[170:173], v[202:205], v[20:23]
	v_mfma_f32_16x16x32_bf16 v[12:15], v[178:181], v[202:205], v[12:15]
	v_mfma_f32_16x16x32_bf16 v[4:7], v[170:173], v[210:213], v[4:7]
	v_mfma_f32_16x16x32_bf16 v[0:3], v[178:181], v[210:213], v[0:3]
	s_setprio 0
	s_barrier
	s_add_i32 s64, s64, 2
	s_add_u32 s62, s62, 0x100
	s_addc_u32 s63, s63, 0
	s_add_u32 s34, s34, 0x10000
	s_addc_u32 s35, s35, 0
	s_cmp_gt_u32 s64, 61
	s_cbranch_scc0 .LBB0_578
	s_branch .Lp5_kdone
